# speedup vs baseline: 1.0156x; 1.0066x over previous
;   __device__ __forceinline__ u16* proj() const { return (u16*)(ws + 185 * MB); }
; #define WAIT_V(n) asm volatile("s_waitcnt vmcnt(%0)" ::"n"(n) : "memory")
; #define LDS_FENCE() asm volatile("s_waitcnt lgkmcnt(0)" ::: "memory")
; template <int EPI> ...
;     ...
;         const int ld = (EPI == EPI_PROJ) ? INW : DFF;
;         u16* gout = p.proj() + (long)(brow + wr * 128 + (lane >> 3)) * ld + bcol + wc * 64 + (lane & 7) * 8;
;         const int wswz = fr & 7, rswz = (lane >> 3) & 7;
; #pragma unroll
;         for (int h = 0; h < 2; ++h) {
; #pragma unroll
;           for (int mm = 0; mm < 4; ++mm)
; #pragma unroll
;             for (int n = 0; n < 4; ++n) {
;               f32x4 v = acc[h * 4 + mm][n] * rs[h * 4 + mm];
;               if constexpr (EPI == EPI_PROJ) {
;                 if (gate) {
; #pragma unroll
;                   for (int j = 0; j < 4; ++j) v[j] = __builtin_amdgcn_rcpf(1.0f + __expf(-v[j]));
;                 }
;               } else {
; #pragma unroll
;                 for (int j = 0; j < 4; ++j) { float r = fmaxf(v[j], 0.f); v[j] = r * r; }
;               }
;               u32x2 o = {pack2(v[0], v[1]), pack2(v[2], v[3])};
;               *(u32x2*)(wst + (mm * 16 + fr) * 128 + (((n * 2 + (fq >> 1)) ^ wswz) << 4) + (fq & 1) * 8) = o;
;             }
;           LDS_FENCE();
;           if (h == 0) WAIT_V(0);
; #pragma unroll
;           for (int i = 0; i < 8; ++i) {
;             const u32x4 d = *(const u32x4*)(wst + (i * 8 + (lane >> 3)) * 128 + (((lane & 7) ^ rswz) << 4));
;             *(u32x4*)(gout + (long)(h * 64 + i * 8) * ld) = d;
;           }
;           LDS_FENCE();
;         }
.Lp1e_16:
	v_cvt_pk_bf16_f32 v212, v64, v65
	v_cvt_pk_bf16_f32 v213, v66, v67
	ds_write_b64 v199, v[212:213] offset:6144
	s_waitcnt lgkmcnt(0)
	s_waitcnt vmcnt(0)
	ds_read_b128 v[222:225], v202
	ds_read_b128 v[226:229], v202 offset:1024
	ds_read_b128 v[230:233], v202 offset:2048
	ds_read_b128 v[234:237], v202 offset:3072
	ds_read_b128 v[238:241], v202 offset:4096
	ds_read_b128 v[242:245], v202 offset:5120
	ds_read_b128 v[246:249], v202 offset:6144
	ds_read_b128 v[250:253], v202 offset:7168
	s_waitcnt lgkmcnt(7)
	global_store_dwordx4 v[204:205], v[222:225], off nt
	s_mov_b32 s4, 0x11000
	v_lshl_add_u64 v[216:217], v[204:205], 0, s[4:5]
	s_waitcnt lgkmcnt(6)
	global_store_dwordx4 v[216:217], v[226:229], off nt
	s_mov_b32 s4, 0x22000
	v_lshl_add_u64 v[218:219], v[204:205], 0, s[4:5]
	s_waitcnt lgkmcnt(5)
	global_store_dwordx4 v[218:219], v[230:233], off nt
	s_mov_b32 s4, 0x33000
	v_lshl_add_u64 v[220:221], v[204:205], 0, s[4:5]
	s_waitcnt lgkmcnt(4)
	global_store_dwordx4 v[220:221], v[234:237], off nt
	s_mov_b32 s4, 0x44000
	v_lshl_add_u64 v[214:215], v[204:205], 0, s[4:5]
	s_waitcnt lgkmcnt(3)
	global_store_dwordx4 v[214:215], v[238:241], off nt
	s_mov_b32 s4, 0x55000
	v_lshl_add_u64 v[216:217], v[204:205], 0, s[4:5]
	s_waitcnt lgkmcnt(2)
	global_store_dwordx4 v[216:217], v[242:245], off nt
	s_mov_b32 s4, 0x66000
	v_lshl_add_u64 v[218:219], v[204:205], 0, s[4:5]
	s_waitcnt lgkmcnt(1)
	global_store_dwordx4 v[218:219], v[246:249], off nt
	s_mov_b32 s4, 0x77000
	v_lshl_add_u64 v[220:221], v[204:205], 0, s[4:5]
	s_waitcnt lgkmcnt(0)
	global_store_dwordx4 v[220:221], v[250:253], off nt
	s_waitcnt lgkmcnt(0)
	s_cmp_gt_i32 s51, 8
	v_pk_mul_f32 v[76:77], v[76:77], v[142:143] op_sel_hi:[1,0]
	v_pk_mul_f32 v[78:79], v[78:79], v[142:143] op_sel_hi:[1,0]
	v_pk_mul_f32 v[68:69], v[68:69], v[142:143] op_sel_hi:[1,0]
	v_pk_mul_f32 v[70:71], v[70:71], v[142:143] op_sel_hi:[1,0]
	s_cbranch_scc0 .Lp1e_17
	v_mul_f32_e32 v76, 0xbfb8aa3b, v76
	v_mul_f32_e32 v77, 0xbfb8aa3b, v77
	v_mul_f32_e32 v78, 0xbfb8aa3b, v78
	v_mul_f32_e32 v79, 0xbfb8aa3b, v79
	v_exp_f32_e32 v76, v76
	v_exp_f32_e32 v77, v77
	v_exp_f32_e32 v78, v78
	v_exp_f32_e32 v79, v79
	v_add_f32_e32 v76, 1.0, v76
	v_add_f32_e32 v77, 1.0, v77
	v_add_f32_e32 v78, 1.0, v78
	v_add_f32_e32 v79, 1.0, v79
	v_rcp_f32_e32 v76, v76
	v_rcp_f32_e32 v77, v77
	v_rcp_f32_e32 v78, v78
	v_rcp_f32_e32 v79, v79

; #define WAIT_V(n) asm volatile("s_waitcnt vmcnt(%0)" ::"n"(n) : "memory")
; #define LDS_FENCE() asm volatile("s_waitcnt lgkmcnt(0)" ::: "memory")
; template <int EPI> ...
;     ...
;           LDS_FENCE();
;           if (h == 0) WAIT_V(0);
; #pragma unroll
;           for (int i = 0; i < 8; ++i) {
;             const u32x4 d = *(const u32x4*)(wst + (i * 8 + (lane >> 3)) * 128 + (((lane & 7) ^ rswz) << 4));
;             *(u32x4*)(gout + (long)(h * 64 + i * 8) * ld) = d;
;           }
;           LDS_FENCE();
.Lp1e_32:
	v_cvt_pk_bf16_f32 v212, v8, v9
	v_cvt_pk_bf16_f32 v213, v10, v11
	ds_write_b64 v199, v[212:213] offset:6144
	s_waitcnt lgkmcnt(0)
	ds_read_b128 v[222:225], v202
	ds_read_b128 v[226:229], v202 offset:1024
	ds_read_b128 v[230:233], v202 offset:2048
	ds_read_b128 v[234:237], v202 offset:3072
	ds_read_b128 v[238:241], v202 offset:4096
	ds_read_b128 v[242:245], v202 offset:5120
	ds_read_b128 v[246:249], v202 offset:6144
	ds_read_b128 v[250:253], v202 offset:7168
	s_mov_b32 s4, 0x88000
	v_lshl_add_u64 v[214:215], v[204:205], 0, s[4:5]
	s_waitcnt lgkmcnt(7)
	global_store_dwordx4 v[214:215], v[222:225], off nt
	s_mov_b32 s4, 0x99000
	v_lshl_add_u64 v[216:217], v[204:205], 0, s[4:5]
	s_waitcnt lgkmcnt(6)
	global_store_dwordx4 v[216:217], v[226:229], off nt
	s_mov_b32 s4, 0xaa000
	v_lshl_add_u64 v[218:219], v[204:205], 0, s[4:5]
	s_waitcnt lgkmcnt(5)
	global_store_dwordx4 v[218:219], v[230:233], off nt
	s_mov_b32 s4, 0xbb000
	v_lshl_add_u64 v[220:221], v[204:205], 0, s[4:5]
	s_waitcnt lgkmcnt(4)
	global_store_dwordx4 v[220:221], v[234:237], off nt
	s_mov_b32 s4, 0xcc000
	v_lshl_add_u64 v[214:215], v[204:205], 0, s[4:5]
	s_waitcnt lgkmcnt(3)
	global_store_dwordx4 v[214:215], v[238:241], off nt
	s_mov_b32 s4, 0xdd000
	v_lshl_add_u64 v[216:217], v[204:205], 0, s[4:5]
	s_waitcnt lgkmcnt(2)
	global_store_dwordx4 v[216:217], v[242:245], off nt
	s_mov_b32 s4, 0xee000
	v_lshl_add_u64 v[218:219], v[204:205], 0, s[4:5]
	s_waitcnt lgkmcnt(1)
	global_store_dwordx4 v[218:219], v[246:249], off nt
	s_mov_b32 s4, 0xff000
	v_lshl_add_u64 v[220:221], v[204:205], 0, s[4:5]
	s_waitcnt lgkmcnt(0)
	global_store_dwordx4 v[220:221], v[250:253], off nt
	s_waitcnt lgkmcnt(0)

; template <int EPI> ...
;     ...
;       unsigned long long sqc[8];
; #pragma unroll
;       for (int m = 0; m < 8; ++m) sqc[m] = ssq_in[pm * 256 + wr * 128 + fr + m * 16];
; #pragma unroll
;       for (int m = 0; m < 8; ++m) rs[m] = rsqrtf((float)sqc[m] * SSQ_UNFIX + 1e-6f);
;     ...
;               f32x4 v = acc[h * 4 + mm][n] * rs[h * 4 + mm];
;               if constexpr (EPI == EPI_PROJ) {
;                 if (gate) {
; #pragma unroll
;                   for (int j = 0; j < 4; ++j) v[j] = __builtin_amdgcn_rcpf(1.0f + __expf(-v[j]));
;                 }
;               } else {
; #pragma unroll
;                 for (int j = 0; j < 4; ++j) { float r = fmaxf(v[j], 0.f); v[j] = r * r; }
.LBB0_674:
	s_waitcnt vmcnt(0)
	v_ffbh_u32_e32 v152, v151
	v_min_u32_e32 v152, 32, v152
	v_lshlrev_b64 v[150:151], v152, v[150:151]
	v_min_u32_e32 v150, 1, v150
	v_or_b32_e32 v150, v151, v150
	v_cvt_f32_u32_e32 v150, v150
	v_sub_u32_e32 v151, 32, v152
	s_lshl_b32 s20, s92, 8
	s_ashr_i32 s21, s20, 31
	v_ldexp_f32 v150, v150, v151
	v_fmamk_f32 v150, v150, 0x30800000, v160
	v_cmp_gt_f32_e32 vcc, s61, v150
	v_mul_f32_e32 v151, 0x4b800000, v150
	v_mov_b32_e32 v157, v2
	v_cndmask_b32_e32 v150, v150, v151, vcc
	v_rsq_f32_e32 v150, v150
	s_mov_b32 s26, s75
	s_mov_b64 s[24:25], s[14:15]
	s_mov_b32 s92, s91
	v_mul_f32_e32 v151, 0x45800000, v150
	v_cndmask_b32_e32 v152, v150, v151, vcc
	v_ffbh_u32_e32 v150, v149
	v_min_u32_e32 v150, 32, v150
	v_lshlrev_b64 v[148:149], v150, v[148:149]
	v_min_u32_e32 v148, 1, v148
	v_or_b32_e32 v148, v149, v148
	v_cvt_f32_u32_e32 v148, v148
	v_sub_u32_e32 v149, 32, v150
	v_pk_mul_f32 v[134:135], v[134:135], v[152:153] op_sel_hi:[1,0]
	v_pk_mul_f32 v[124:125], v[124:125], v[152:153] op_sel_hi:[1,0]
	v_ldexp_f32 v148, v148, v149
	v_fmamk_f32 v148, v148, 0x30800000, v160
	v_cmp_gt_f32_e32 vcc, s61, v148
	v_mul_f32_e32 v149, 0x4b800000, v148
	v_max_f32_e32 v134, 0, v134
	v_cndmask_b32_e32 v148, v148, v149, vcc
	v_rsq_f32_e32 v148, v148
	v_max_f32_e32 v135, 0, v135
	v_pk_mul_f32 v[126:127], v[126:127], v[152:153] op_sel_hi:[1,0]
	v_max_f32_e32 v124, 0, v124
	v_mul_f32_e32 v149, 0x45800000, v148
	v_cndmask_b32_e32 v150, v148, v149, vcc
	v_ffbh_u32_e32 v148, v147
	v_min_u32_e32 v148, 32, v148
	v_lshlrev_b64 v[146:147], v148, v[146:147]
	v_min_u32_e32 v146, 1, v146
	v_or_b32_e32 v146, v147, v146
	v_cvt_f32_u32_e32 v146, v146
	v_sub_u32_e32 v147, 32, v148
	v_max_f32_e32 v125, 0, v125
	v_pk_mul_f32 v[134:135], v[134:135], v[134:135]
	v_ldexp_f32 v146, v146, v147
	v_fmamk_f32 v146, v146, 0x30800000, v160
	v_cmp_gt_f32_e32 vcc, s61, v146
	v_mul_f32_e32 v147, 0x4b800000, v146
	v_pk_mul_f32 v[124:125], v[124:125], v[124:125]
	v_cndmask_b32_e32 v146, v146, v147, vcc
	v_rsq_f32_e32 v146, v146
	v_max_f32_e32 v126, 0, v126
	v_max_f32_e32 v127, 0, v127
	v_pk_mul_f32 v[126:127], v[126:127], v[126:127]
	v_mul_f32_e32 v147, 0x45800000, v146
	v_cndmask_b32_e32 v148, v146, v147, vcc
	v_ffbh_u32_e32 v146, v145
	v_min_u32_e32 v146, 32, v146
	v_lshlrev_b64 v[144:145], v146, v[144:145]
	v_min_u32_e32 v144, 1, v144
	v_or_b32_e32 v144, v145, v144
	v_cvt_f32_u32_e32 v144, v144
	v_sub_u32_e32 v145, 32, v146
	v_pk_mul_f32 v[132:133], v[132:133], v[152:153] op_sel_hi:[1,0]
	v_pk_mul_f32 v[128:129], v[128:129], v[152:153] op_sel_hi:[1,0]
	v_ldexp_f32 v144, v144, v145
	v_fmamk_f32 v144, v144, 0x30800000, v160
	v_cmp_gt_f32_e32 vcc, s61, v144
	v_mul_f32_e32 v145, 0x4b800000, v144
	v_pk_mul_f32 v[120:121], v[120:121], v[152:153] op_sel_hi:[1,0]
	v_cndmask_b32_e32 v144, v144, v145, vcc
	v_rsq_f32_e32 v144, v144
	v_max_f32_e32 v132, 0, v132
	v_max_f32_e32 v133, 0, v133
	v_max_f32_e32 v128, 0, v128
	v_mul_f32_e32 v145, 0x45800000, v144
	v_cndmask_b32_e32 v146, v144, v145, vcc
	v_ffbh_u32_e32 v144, v143
	v_min_u32_e32 v144, 32, v144
	v_lshlrev_b64 v[142:143], v144, v[142:143]
	v_min_u32_e32 v142, 1, v142
	v_or_b32_e32 v142, v143, v142
	v_cvt_f32_u32_e32 v142, v142
	v_sub_u32_e32 v143, 32, v144
	v_max_f32_e32 v129, 0, v129
	v_pk_mul_f32 v[122:123], v[122:123], v[152:153] op_sel_hi:[1,0]
	v_ldexp_f32 v142, v142, v143
	v_fmamk_f32 v142, v142, 0x30800000, v160
	v_cmp_gt_f32_e32 vcc, s61, v142
	v_mul_f32_e32 v143, 0x4b800000, v142
	v_max_f32_e32 v120, 0, v120
	v_cndmask_b32_e32 v142, v142, v143, vcc
	v_rsq_f32_e32 v142, v142
	v_max_f32_e32 v121, 0, v121
	v_pk_mul_f32 v[132:133], v[132:133], v[132:133]
	v_pk_mul_f32 v[128:129], v[128:129], v[128:129]
	v_mul_f32_e32 v143, 0x45800000, v142
	v_cndmask_b32_e32 v144, v142, v143, vcc
	v_ffbh_u32_e32 v142, v141
	v_min_u32_e32 v142, 32, v142
	v_lshlrev_b64 v[140:141], v142, v[140:141]
	v_min_u32_e32 v140, 1, v140
	v_or_b32_e32 v140, v141, v140
	v_cvt_f32_u32_e32 v140, v140
	v_sub_u32_e32 v141, 32, v142
	v_pk_mul_f32 v[120:121], v[120:121], v[120:121]
	v_max_f32_e32 v122, 0, v122
	v_ldexp_f32 v140, v140, v141
	v_fmamk_f32 v140, v140, 0x30800000, v160
	v_cmp_gt_f32_e32 vcc, s61, v140
	v_mul_f32_e32 v141, 0x4b800000, v140
	v_max_f32_e32 v123, 0, v123
	v_cndmask_b32_e32 v140, v140, v141, vcc
	v_rsq_f32_e32 v140, v140
	v_cvt_pk_bf16_f32 v128, v128, v129
	v_pk_mul_f32 v[122:123], v[122:123], v[122:123]
	s_mov_b32 s93, s90
	v_mul_f32_e32 v141, 0x45800000, v140
	v_cndmask_b32_e32 v142, v140, v141, vcc
	v_ffbh_u32_e32 v140, v139
	v_min_u32_e32 v140, 32, v140
	v_lshlrev_b64 v[138:139], v140, v[138:139]
	v_min_u32_e32 v138, 1, v138
	v_or_b32_e32 v138, v139, v138
	v_cvt_f32_u32_e32 v138, v138
	v_sub_u32_e32 v139, 32, v140
	v_mov_b32_e32 v141, v3
	v_ldexp_f32 v138, v138, v139
	v_fmamk_f32 v138, v138, 0x30800000, v160
	v_cmp_gt_f32_e32 vcc, s61, v138
	v_mul_f32_e32 v139, 0x4b800000, v138
	v_bfe_u32 v147, v141, 3, 3
	v_cndmask_b32_e32 v138, v138, v139, vcc
	v_rsq_f32_e32 v138, v138
	v_lshrrev_b32_e32 v151, 1, v141
	v_and_b32_e32 v151, 8, v151
	v_and_b32_e32 v145, 0xc0, v141
	v_mul_f32_e32 v139, 0x45800000, v138
	v_cndmask_b32_e32 v140, v138, v139, vcc
	v_ffbh_u32_e32 v138, v137
	v_min_u32_e32 v138, 32, v138
	v_lshlrev_b64 v[136:137], v138, v[136:137]
	v_min_u32_e32 v136, 1, v136
	v_or_b32_e32 v136, v137, v136
	v_cvt_f32_u32_e32 v136, v136
	v_sub_u32_e32 v137, 32, v138
	v_lshlrev_b32_e32 v139, 7, v141
	v_bfe_u32 v149, v141, 5, 1
	v_ldexp_f32 v136, v136, v137
	v_fmamk_f32 v136, v136, 0x30800000, v160
	v_cmp_gt_f32_e32 vcc, s61, v136
	v_mul_f32_e32 v137, 0x4b800000, v136
	v_lshlrev_b32_e32 v156, 1, v145
	v_cndmask_b32_e32 v136, v136, v137, vcc
;   __device__ __forceinline__ u16* proj() const { return (u16*)(ws + 185 * MB); }
; template <int EPI> ...
;     ...
;         u16* gout = p.proj() + (long)(brow + wr * 128 + (lane >> 3)) * ld + bcol + wc * 64 + (lane & 7) * 8;
;         const int wswz = fr & 7, rswz = (lane >> 3) & 7;
; #pragma unroll
;         for (int h = 0; h < 2; ++h) {
; #pragma unroll
;           for (int mm = 0; mm < 4; ++mm)
; #pragma unroll
;             for (int n = 0; n < 4; ++n) {
;               f32x4 v = acc[h * 4 + mm][n] * rs[h * 4 + mm];
;               if constexpr (EPI == EPI_PROJ) {
;                 if (gate) {
; #pragma unroll
;                   for (int j = 0; j < 4; ++j) v[j] = __builtin_amdgcn_rcpf(1.0f + __expf(-v[j]));
;                 }
;               } else {
; #pragma unroll
;                 for (int j = 0; j < 4; ++j) { float r = fmaxf(v[j], 0.f); v[j] = r * r; }
;               }
;               u32x2 o = {pack2(v[0], v[1]), pack2(v[2], v[3])};
;               *(u32x2*)(wst + (mm * 16 + fr) * 128 + (((n * 2 + (fq >> 1)) ^ wswz) << 4) + (fq & 1) * 8) = o;
	v_rsq_f32_e32 v136, v136
	v_and_b32_e32 v145, 7, v141
	v_pk_mul_f32 v[94:95], v[94:95], v[148:149] op_sel_hi:[1,0]
	v_pk_mul_f32 v[92:93], v[92:93], v[148:149] op_sel_hi:[1,0]
	v_mul_f32_e32 v137, 0x45800000, v136
	v_cndmask_b32_e32 v138, v136, v137, vcc
	v_and_b32_e32 v136, 0xffffe000, v139
	v_add_u32_e32 v143, 0x10000, v136
	v_ashrrev_i32_e32 v136, 1, v141
	v_and_b32_e32 v136, 0xffffff80, v136
	v_add_u32_e32 v136, s22, v136
	v_or_b32_e32 v136, v136, v147
	v_ashrrev_i32_e32 v137, 31, v136
	v_and_b32_e32 v139, 0x780, v139
	v_lshlrev_b64 v[136:137], 13, v[136:137]
	v_or3_b32 v151, v143, v139, v151
	v_lshlrev_b32_e32 v139, 7, v147
	v_bitop3_b32 v147, v147, v141, 7 bitop3:0x78
	v_lshl_add_u64 v[136:137], s[38:39], 0, v[136:137]
	v_lshlrev_b32_e32 v147, 4, v147
	v_lshl_add_u64 v[136:137], s[20:21], 1, v[136:137]
	v_pk_mul_f32 v[110:111], v[110:111], v[150:151] op_sel_hi:[1,0]
	v_pk_mul_f32 v[108:109], v[108:109], v[150:151] op_sel_hi:[1,0]
	v_pk_mul_f32 v[78:79], v[78:79], v[146:147] op_sel_hi:[1,0]
	v_pk_mul_f32 v[76:77], v[76:77], v[146:147] op_sel_hi:[1,0]
	v_lshl_add_u64 v[136:137], v[136:137], 0, v[156:157]
	v_lshlrev_b32_e32 v156, 4, v145
	v_max_f32_e32 v108, 0, v108
	v_max_f32_e32 v109, 0, v109
	v_max_f32_e32 v110, 0, v110
	v_max_f32_e32 v111, 0, v111
	v_max_f32_e32 v92, 0, v92
	v_max_f32_e32 v93, 0, v93
	v_max_f32_e32 v94, 0, v94
	v_max_f32_e32 v95, 0, v95
	v_max_f32_e32 v76, 0, v76
	v_max_f32_e32 v77, 0, v77
	v_max_f32_e32 v78, 0, v78
	v_max_f32_e32 v79, 0, v79
	v_lshl_add_u64 v[136:137], v[136:137], 0, v[156:157]
	v_cvt_pk_bf16_f32 v157, v134, v135
	v_cvt_pk_bf16_f32 v134, v124, v125
	v_bitop3_b32 v124, v149, v145, 2 bitop3:0x36
	v_pk_mul_f32 v[108:109], v[108:109], v[108:109]
	v_pk_mul_f32 v[110:111], v[110:111], v[110:111]
	v_pk_mul_f32 v[92:93], v[92:93], v[92:93]
	v_pk_mul_f32 v[94:95], v[94:95], v[94:95]
	v_pk_mul_f32 v[76:77], v[76:77], v[76:77]
	v_pk_mul_f32 v[78:79], v[78:79], v[78:79]
	v_cvt_pk_bf16_f32 v135, v126, v127
	v_lshl_or_b32 v124, v124, 4, v151
	v_pk_mul_f32 v[126:127], v[130:131], v[152:153] op_sel_hi:[1,0]
	v_cvt_pk_bf16_f32 v108, v108, v109
	v_cvt_pk_bf16_f32 v109, v110, v111
	v_cvt_pk_bf16_f32 v92, v92, v93
	v_cvt_pk_bf16_f32 v93, v94, v95
	v_cvt_pk_bf16_f32 v76, v76, v77
	v_cvt_pk_bf16_f32 v77, v78, v79
	v_max_f32_e32 v126, 0, v126
	v_max_f32_e32 v127, 0, v127
	v_pk_mul_f32 v[118:119], v[118:119], v[150:151] op_sel_hi:[1,0]
	v_pk_mul_f32 v[116:117], v[116:117], v[150:151] op_sel_hi:[1,0]
	ds_write2st64_b64 v124, v[134:135], v[108:109] offset1:4
	v_pk_mul_f32 v[108:109], v[114:115], v[150:151] op_sel_hi:[1,0]
	v_pk_mul_f32 v[110:111], v[112:113], v[150:151] op_sel_hi:[1,0]
	v_pk_mul_f32 v[106:107], v[106:107], v[150:151] op_sel_hi:[1,0]
	v_pk_mul_f32 v[104:105], v[104:105], v[150:151] op_sel_hi:[1,0]
	v_pk_mul_f32 v[102:103], v[102:103], v[148:149] op_sel_hi:[1,0]
	v_pk_mul_f32 v[100:101], v[100:101], v[148:149] op_sel_hi:[1,0]
	v_pk_mul_f32 v[94:95], v[98:99], v[148:149] op_sel_hi:[1,0]
	v_pk_mul_f32 v[96:97], v[96:97], v[148:149] op_sel_hi:[1,0]
	v_pk_mul_f32 v[90:91], v[90:91], v[148:149] op_sel_hi:[1,0]
	v_pk_mul_f32 v[88:89], v[88:89], v[148:149] op_sel_hi:[1,0]
	v_pk_mul_f32 v[86:87], v[86:87], v[146:147] op_sel_hi:[1,0]
	v_pk_mul_f32 v[84:85], v[84:85], v[146:147] op_sel_hi:[1,0]
	ds_write2st64_b64 v124, v[92:93], v[76:77] offset0:8 offset1:12
	v_pk_mul_f32 v[76:77], v[82:83], v[146:147] op_sel_hi:[1,0]
	v_pk_mul_f32 v[78:79], v[80:81], v[146:147] op_sel_hi:[1,0]
	v_pk_mul_f32 v[74:75], v[74:75], v[146:147] op_sel_hi:[1,0]
	v_pk_mul_f32 v[72:73], v[72:73], v[146:147] op_sel_hi:[1,0]
	v_pk_mul_f32 v[126:127], v[126:127], v[126:127]
	v_max_f32_e32 v116, 0, v116
	v_max_f32_e32 v117, 0, v117
	v_max_f32_e32 v118, 0, v118
	v_max_f32_e32 v119, 0, v119
	v_max_f32_e32 v110, 0, v110
	v_max_f32_e32 v111, 0, v111
	v_max_f32_e32 v108, 0, v108
	v_max_f32_e32 v109, 0, v109
	v_max_f32_e32 v104, 0, v104
	v_max_f32_e32 v105, 0, v105
	v_max_f32_e32 v106, 0, v106
	v_max_f32_e32 v107, 0, v107
	v_max_f32_e32 v100, 0, v100
	v_max_f32_e32 v101, 0, v101
	v_max_f32_e32 v102, 0, v102
	v_max_f32_e32 v103, 0, v103
	v_max_f32_e32 v96, 0, v96
	v_max_f32_e32 v97, 0, v97
	v_max_f32_e32 v94, 0, v94
	v_max_f32_e32 v95, 0, v95
	v_max_f32_e32 v88, 0, v88
	v_max_f32_e32 v89, 0, v89
	v_max_f32_e32 v90, 0, v90
	v_max_f32_e32 v91, 0, v91
	v_max_f32_e32 v84, 0, v84
	v_max_f32_e32 v85, 0, v85
	v_max_f32_e32 v86, 0, v86
	v_max_f32_e32 v87, 0, v87
	v_max_f32_e32 v78, 0, v78
	v_max_f32_e32 v79, 0, v79
	v_max_f32_e32 v76, 0, v76
	v_max_f32_e32 v77, 0, v77
	v_max_f32_e32 v72, 0, v72
	v_max_f32_e32 v73, 0, v73
	v_max_f32_e32 v74, 0, v74
	v_max_f32_e32 v75, 0, v75
	v_cvt_pk_bf16_f32 v156, v132, v133
	v_bitop3_b32 v132, v149, v141, 7 bitop3:0x78
	v_cvt_pk_bf16_f32 v129, v126, v127
	v_bitop3_b32 v125, v149, v145, 4 bitop3:0x36
	v_cvt_pk_bf16_f32 v126, v120, v121
	v_bitop3_b32 v120, v149, v145, 6 bitop3:0x36
	v_pk_mul_f32 v[116:117], v[116:117], v[116:117]
	v_pk_mul_f32 v[118:119], v[118:119], v[118:119]
	v_pk_mul_f32 v[110:111], v[110:111], v[110:111]
	v_pk_mul_f32 v[108:109], v[108:109], v[108:109]
	v_pk_mul_f32 v[104:105], v[104:105], v[104:105]
	v_pk_mul_f32 v[106:107], v[106:107], v[106:107]
	v_pk_mul_f32 v[100:101], v[100:101], v[100:101]
	v_pk_mul_f32 v[102:103], v[102:103], v[102:103]
	v_pk_mul_f32 v[96:97], v[96:97], v[96:97]
	v_pk_mul_f32 v[94:95], v[94:95], v[94:95]
	v_pk_mul_f32 v[88:89], v[88:89], v[88:89]
	v_pk_mul_f32 v[90:91], v[90:91], v[90:91]
	v_pk_mul_f32 v[84:85], v[84:85], v[84:85]
	v_pk_mul_f32 v[86:87], v[86:87], v[86:87]
	v_pk_mul_f32 v[78:79], v[78:79], v[78:79]
	v_pk_mul_f32 v[76:77], v[76:77], v[76:77]
	v_pk_mul_f32 v[72:73], v[72:73], v[72:73]
	v_pk_mul_f32 v[74:75], v[74:75], v[74:75]
	v_lshl_or_b32 v132, v132, 4, v151
	v_lshl_or_b32 v125, v125, 4, v151
	v_cvt_pk_bf16_f32 v127, v122, v123
	v_lshl_or_b32 v120, v120, 4, v151
	v_cvt_pk_bf16_f32 v116, v116, v117
	v_cvt_pk_bf16_f32 v117, v118, v119
	v_cvt_pk_bf16_f32 v110, v110, v111
	v_cvt_pk_bf16_f32 v111, v108, v109
	v_cvt_pk_bf16_f32 v104, v104, v105
	v_cvt_pk_bf16_f32 v105, v106, v107
	v_cvt_pk_bf16_f32 v100, v100, v101
	v_cvt_pk_bf16_f32 v101, v102, v103
	v_cvt_pk_bf16_f32 v96, v96, v97
	v_cvt_pk_bf16_f32 v97, v94, v95
	v_cvt_pk_bf16_f32 v88, v88, v89
	v_cvt_pk_bf16_f32 v89, v90, v91
	v_cvt_pk_bf16_f32 v84, v84, v85
	v_cvt_pk_bf16_f32 v85, v86, v87
	v_cvt_pk_bf16_f32 v78, v78, v79
	v_cvt_pk_bf16_f32 v79, v76, v77
	v_cvt_pk_bf16_f32 v72, v72, v73
	v_cvt_pk_bf16_f32 v73, v74, v75
	ds_write2st64_b64 v132, v[156:157], v[116:117] offset1:4
	ds_write2st64_b64 v125, v[128:129], v[110:111] offset1:4
	ds_write2st64_b64 v120, v[126:127], v[104:105] offset1:4
	ds_write2st64_b64 v132, v[100:101], v[84:85] offset0:8 offset1:12
	ds_write2st64_b64 v125, v[96:97], v[78:79] offset0:8 offset1:12
	ds_write2st64_b64 v120, v[88:89], v[72:73] offset0:8 offset1:12
	s_waitcnt lgkmcnt(0)
; #define WAIT_V(n) asm volatile("s_waitcnt vmcnt(%0)" ::"n"(n) : "memory")
; #define LDS_FENCE() asm volatile("s_waitcnt lgkmcnt(0)" ::: "memory")
; template <int EPI> ...
;     ...
;               f32x4 v = acc[h * 4 + mm][n] * rs[h * 4 + mm];
;               if constexpr (EPI == EPI_PROJ) {
;                 if (gate) {
; #pragma unroll
;                   for (int j = 0; j < 4; ++j) v[j] = __builtin_amdgcn_rcpf(1.0f + __expf(-v[j]));
;                 }
;               } else {
; #pragma unroll
;                 for (int j = 0; j < 4; ++j) { float r = fmaxf(v[j], 0.f); v[j] = r * r; }
;     ...
;           LDS_FENCE();
;           if (h == 0) WAIT_V(0);
; #pragma unroll
;           for (int i = 0; i < 8; ++i) {
;             const u32x4 d = *(const u32x4*)(wst + (i * 8 + (lane >> 3)) * 128 + (((lane & 7) ^ rswz) << 4));
;             *(u32x4*)(gout + (long)(h * 64 + i * 8) * ld) = d;
	v_or3_b32 v139, v143, v139, v147
	s_waitcnt vmcnt(0)
	ds_read_b128 v[72:75], v139
	v_add_co_u32_e32 v76, vcc, s68, v136
	s_mov_b32 s20, 0x50000
	s_nop 0
	v_addc_co_u32_e32 v77, vcc, 0, v137, vcc
	s_waitcnt lgkmcnt(0)
	global_store_dwordx4 v[136:137], v[72:75], off nt
	ds_read_b128 v[72:75], v139 offset:1024
	v_pk_mul_f32 v[70:71], v[70:71], v[144:145] op_sel_hi:[1,0]
	v_pk_mul_f32 v[68:69], v[68:69], v[144:145] op_sel_hi:[1,0]
	v_pk_mul_f32 v[66:67], v[66:67], v[144:145] op_sel_hi:[1,0]
	v_pk_mul_f32 v[64:65], v[64:65], v[144:145] op_sel_hi:[1,0]
	s_waitcnt lgkmcnt(0)
	global_store_dwordx4 v[76:77], v[72:75], off nt
	ds_read_b128 v[72:75], v139 offset:2048
	v_add_co_u32_e32 v76, vcc, s87, v136
	v_pk_mul_f32 v[62:63], v[62:63], v[144:145] op_sel_hi:[1,0]
	s_nop 0
	v_addc_co_u32_e32 v77, vcc, 0, v137, vcc
	s_waitcnt lgkmcnt(0)
	global_store_dwordx4 v[76:77], v[72:75], off nt
	ds_read_b128 v[72:75], v139 offset:3072
	v_add_co_u32_e32 v76, vcc, s64, v136
	v_pk_mul_f32 v[60:61], v[60:61], v[144:145] op_sel_hi:[1,0]
	s_nop 0
	v_addc_co_u32_e32 v77, vcc, 0, v137, vcc
	s_waitcnt lgkmcnt(0)
	global_store_dwordx4 v[76:77], v[72:75], off nt
	ds_read_b128 v[72:75], v139 offset:4096
	v_add_co_u32_e32 v76, vcc, s89, v136
	v_pk_mul_f32 v[58:59], v[58:59], v[144:145] op_sel_hi:[1,0]
	s_nop 0
	v_addc_co_u32_e32 v77, vcc, 0, v137, vcc
	s_waitcnt lgkmcnt(0)
	global_store_dwordx4 v[76:77], v[72:75], off nt
	ds_read_b128 v[72:75], v139 offset:5120
	v_add_co_u32_e32 v76, vcc, s20, v136
	s_mov_b32 s20, 0x60000
	s_nop 0
	v_addc_co_u32_e32 v77, vcc, 0, v137, vcc
	s_waitcnt lgkmcnt(0)
	global_store_dwordx4 v[76:77], v[72:75], off nt
	ds_read_b128 v[72:75], v139 offset:6144
	v_add_co_u32_e32 v76, vcc, s20, v136
	s_mov_b32 s20, 0x70000
	s_nop 0
	v_addc_co_u32_e32 v77, vcc, 0, v137, vcc
	s_waitcnt lgkmcnt(0)
	global_store_dwordx4 v[76:77], v[72:75], off nt
	ds_read_b128 v[72:75], v139 offset:7168
	v_pk_mul_f32 v[56:57], v[56:57], v[144:145] op_sel_hi:[1,0]
	v_pk_mul_f32 v[54:55], v[54:55], v[142:143] op_sel_hi:[1,0]
	v_pk_mul_f32 v[52:53], v[52:53], v[142:143] op_sel_hi:[1,0]
	v_pk_mul_f32 v[50:51], v[50:51], v[142:143] op_sel_hi:[1,0]
	v_pk_mul_f32 v[48:49], v[48:49], v[142:143] op_sel_hi:[1,0]
	v_pk_mul_f32 v[46:47], v[46:47], v[142:143] op_sel_hi:[1,0]
	v_pk_mul_f32 v[44:45], v[44:45], v[142:143] op_sel_hi:[1,0]
	v_pk_mul_f32 v[42:43], v[42:43], v[142:143] op_sel_hi:[1,0]
	v_pk_mul_f32 v[40:41], v[40:41], v[142:143] op_sel_hi:[1,0]
	v_pk_mul_f32 v[38:39], v[38:39], v[140:141] op_sel_hi:[1,0]
	v_pk_mul_f32 v[36:37], v[36:37], v[140:141] op_sel_hi:[1,0]
	v_pk_mul_f32 v[34:35], v[34:35], v[140:141] op_sel_hi:[1,0]
	v_pk_mul_f32 v[32:33], v[32:33], v[140:141] op_sel_hi:[1,0]
	v_pk_mul_f32 v[30:31], v[30:31], v[140:141] op_sel_hi:[1,0]
	v_pk_mul_f32 v[28:29], v[28:29], v[140:141] op_sel_hi:[1,0]
	v_pk_mul_f32 v[26:27], v[26:27], v[140:141] op_sel_hi:[1,0]
	v_pk_mul_f32 v[24:25], v[24:25], v[140:141] op_sel_hi:[1,0]
	v_pk_mul_f32 v[22:23], v[22:23], v[138:139] op_sel_hi:[1,0]
	v_pk_mul_f32 v[20:21], v[20:21], v[138:139] op_sel_hi:[1,0]
	v_pk_mul_f32 v[18:19], v[18:19], v[138:139] op_sel_hi:[1,0]
	v_pk_mul_f32 v[16:17], v[16:17], v[138:139] op_sel_hi:[1,0]
	v_pk_mul_f32 v[14:15], v[14:15], v[138:139] op_sel_hi:[1,0]
	v_pk_mul_f32 v[12:13], v[12:13], v[138:139] op_sel_hi:[1,0]
	v_pk_mul_f32 v[10:11], v[10:11], v[138:139] op_sel_hi:[1,0]
	v_pk_mul_f32 v[8:9], v[8:9], v[138:139] op_sel_hi:[1,0]
	v_add_co_u32_e32 v76, vcc, s20, v136
	v_max_f32_e32 v68, 0, v68
	v_max_f32_e32 v69, 0, v69
	v_max_f32_e32 v70, 0, v70
	v_max_f32_e32 v71, 0, v71
	v_max_f32_e32 v64, 0, v64
	v_max_f32_e32 v65, 0, v65
	v_max_f32_e32 v66, 0, v66
	v_max_f32_e32 v67, 0, v67
	v_max_f32_e32 v60, 0, v60
	v_max_f32_e32 v61, 0, v61
	v_max_f32_e32 v62, 0, v62
	v_max_f32_e32 v63, 0, v63
	v_max_f32_e32 v56, 0, v56
	v_max_f32_e32 v57, 0, v57
	v_max_f32_e32 v58, 0, v58
	v_max_f32_e32 v59, 0, v59
	v_max_f32_e32 v52, 0, v52
	v_max_f32_e32 v53, 0, v53
	v_max_f32_e32 v54, 0, v54
	v_max_f32_e32 v55, 0, v55
	v_max_f32_e32 v48, 0, v48
	v_max_f32_e32 v49, 0, v49
	v_max_f32_e32 v50, 0, v50
	v_max_f32_e32 v51, 0, v51
	v_max_f32_e32 v44, 0, v44
	v_max_f32_e32 v45, 0, v45
	v_max_f32_e32 v46, 0, v46
	v_max_f32_e32 v47, 0, v47
	v_max_f32_e32 v40, 0, v40
	v_max_f32_e32 v41, 0, v41
	v_max_f32_e32 v42, 0, v42
	v_max_f32_e32 v43, 0, v43
	v_max_f32_e32 v36, 0, v36
	v_max_f32_e32 v37, 0, v37
	v_max_f32_e32 v38, 0, v38
	v_max_f32_e32 v39, 0, v39
	v_max_f32_e32 v32, 0, v32
	v_max_f32_e32 v33, 0, v33
	v_max_f32_e32 v34, 0, v34
	v_max_f32_e32 v35, 0, v35
	v_max_f32_e32 v28, 0, v28
	v_max_f32_e32 v29, 0, v29
	v_max_f32_e32 v30, 0, v30
	v_max_f32_e32 v31, 0, v31
	v_max_f32_e32 v24, 0, v24
	v_max_f32_e32 v25, 0, v25
	v_max_f32_e32 v26, 0, v26
	v_max_f32_e32 v27, 0, v27
	v_max_f32_e32 v20, 0, v20
	v_max_f32_e32 v21, 0, v21
	v_max_f32_e32 v22, 0, v22
	v_max_f32_e32 v23, 0, v23
	v_max_f32_e32 v16, 0, v16
	v_max_f32_e32 v17, 0, v17
	v_max_f32_e32 v18, 0, v18
	v_max_f32_e32 v19, 0, v19
	v_max_f32_e32 v12, 0, v12
	v_max_f32_e32 v13, 0, v13
	v_max_f32_e32 v14, 0, v14
	v_max_f32_e32 v15, 0, v15
	v_max_f32_e32 v8, 0, v8
	v_max_f32_e32 v9, 0, v9
	v_max_f32_e32 v10, 0, v10
	v_max_f32_e32 v11, 0, v11
	v_addc_co_u32_e32 v77, vcc, 0, v137, vcc
	v_pk_mul_f32 v[68:69], v[68:69], v[68:69]
	v_pk_mul_f32 v[70:71], v[70:71], v[70:71]
	v_pk_mul_f32 v[64:65], v[64:65], v[64:65]
	v_pk_mul_f32 v[66:67], v[66:67], v[66:67]
	v_pk_mul_f32 v[60:61], v[60:61], v[60:61]
	v_pk_mul_f32 v[62:63], v[62:63], v[62:63]
	v_pk_mul_f32 v[56:57], v[56:57], v[56:57]
	v_pk_mul_f32 v[58:59], v[58:59], v[58:59]
	v_pk_mul_f32 v[52:53], v[52:53], v[52:53]
	v_pk_mul_f32 v[54:55], v[54:55], v[54:55]
	v_pk_mul_f32 v[48:49], v[48:49], v[48:49]
	v_pk_mul_f32 v[50:51], v[50:51], v[50:51]
	v_pk_mul_f32 v[44:45], v[44:45], v[44:45]
	v_pk_mul_f32 v[46:47], v[46:47], v[46:47]
	v_pk_mul_f32 v[40:41], v[40:41], v[40:41]
	v_pk_mul_f32 v[42:43], v[42:43], v[42:43]
	v_pk_mul_f32 v[36:37], v[36:37], v[36:37]
	v_pk_mul_f32 v[38:39], v[38:39], v[38:39]
	v_pk_mul_f32 v[32:33], v[32:33], v[32:33]
	v_pk_mul_f32 v[34:35], v[34:35], v[34:35]
	v_pk_mul_f32 v[28:29], v[28:29], v[28:29]
	v_pk_mul_f32 v[30:31], v[30:31], v[30:31]
	v_pk_mul_f32 v[24:25], v[24:25], v[24:25]
	v_pk_mul_f32 v[26:27], v[26:27], v[26:27]
	v_pk_mul_f32 v[20:21], v[20:21], v[20:21]
	v_pk_mul_f32 v[22:23], v[22:23], v[22:23]
	v_pk_mul_f32 v[16:17], v[16:17], v[16:17]
	v_pk_mul_f32 v[18:19], v[18:19], v[18:19]
	v_pk_mul_f32 v[12:13], v[12:13], v[12:13]
	v_pk_mul_f32 v[14:15], v[14:15], v[14:15]
	v_pk_mul_f32 v[8:9], v[8:9], v[8:9]
	v_pk_mul_f32 v[10:11], v[10:11], v[10:11]
	s_waitcnt lgkmcnt(0)
; #define WAIT_V(n) asm volatile("s_waitcnt vmcnt(%0)" ::"n"(n) : "memory")
; #define LDS_FENCE() asm volatile("s_waitcnt lgkmcnt(0)" ::: "memory")
; template <int EPI> ...
;     ...
;               u32x2 o = {pack2(v[0], v[1]), pack2(v[2], v[3])};
;               *(u32x2*)(wst + (mm * 16 + fr) * 128 + (((n * 2 + (fq >> 1)) ^ wswz) << 4) + (fq & 1) * 8) = o;
;             }
;           LDS_FENCE();
;           if (h == 0) WAIT_V(0);
; #pragma unroll
;           for (int i = 0; i < 8; ++i) {
;             const u32x4 d = *(const u32x4*)(wst + (i * 8 + (lane >> 3)) * 128 + (((lane & 7) ^ rswz) << 4));
;             *(u32x4*)(gout + (long)(h * 64 + i * 8) * ld) = d;
;           }
;           LDS_FENCE();
;         }
	global_store_dwordx4 v[76:77], v[72:75], off nt
	v_cvt_pk_bf16_f32 v68, v68, v69
	v_cvt_pk_bf16_f32 v69, v70, v71
	v_cvt_pk_bf16_f32 v64, v64, v65
	v_cvt_pk_bf16_f32 v65, v66, v67
	v_cvt_pk_bf16_f32 v60, v60, v61
	v_cvt_pk_bf16_f32 v61, v62, v63
	v_cvt_pk_bf16_f32 v56, v56, v57
	v_cvt_pk_bf16_f32 v57, v58, v59
	v_cvt_pk_bf16_f32 v52, v52, v53
	v_cvt_pk_bf16_f32 v53, v54, v55
	v_cvt_pk_bf16_f32 v48, v48, v49
	v_cvt_pk_bf16_f32 v49, v50, v51
	v_cvt_pk_bf16_f32 v44, v44, v45
	v_cvt_pk_bf16_f32 v45, v46, v47
	v_cvt_pk_bf16_f32 v40, v40, v41
	v_cvt_pk_bf16_f32 v41, v42, v43
	v_cvt_pk_bf16_f32 v36, v36, v37
	v_cvt_pk_bf16_f32 v37, v38, v39
	v_cvt_pk_bf16_f32 v32, v32, v33
	v_cvt_pk_bf16_f32 v33, v34, v35
	v_cvt_pk_bf16_f32 v28, v28, v29
	v_cvt_pk_bf16_f32 v29, v30, v31
	v_cvt_pk_bf16_f32 v24, v24, v25
	v_cvt_pk_bf16_f32 v25, v26, v27
	v_cvt_pk_bf16_f32 v20, v20, v21
	v_cvt_pk_bf16_f32 v21, v22, v23
	v_cvt_pk_bf16_f32 v16, v16, v17
	v_cvt_pk_bf16_f32 v17, v18, v19
	v_cvt_pk_bf16_f32 v12, v12, v13
	v_cvt_pk_bf16_f32 v13, v14, v15
	v_cvt_pk_bf16_f32 v8, v8, v9
	v_cvt_pk_bf16_f32 v9, v10, v11
	s_waitcnt lgkmcnt(0)
	ds_write2st64_b64 v132, v[68:69], v[52:53] offset1:4
	ds_write2st64_b64 v124, v[64:65], v[48:49] offset1:4
	ds_write2st64_b64 v125, v[60:61], v[44:45] offset1:4
	ds_write2st64_b64 v120, v[56:57], v[40:41] offset1:4
	ds_write2st64_b64 v132, v[36:37], v[20:21] offset0:8 offset1:12
	ds_write2st64_b64 v124, v[32:33], v[16:17] offset0:8 offset1:12
	ds_write2st64_b64 v125, v[28:29], v[12:13] offset0:8 offset1:12
	ds_write2st64_b64 v120, v[24:25], v[8:9] offset0:8 offset1:12
	s_waitcnt lgkmcnt(0)
	ds_read_b128 v[8:11], v139
	s_mov_b32 s20, 0x80000
	v_add_co_u32_e32 v12, vcc, s20, v136
	s_mov_b32 s20, 0x90000
	s_nop 0
	v_addc_co_u32_e32 v13, vcc, 0, v137, vcc
	s_waitcnt lgkmcnt(0)
	global_store_dwordx4 v[12:13], v[8:11], off nt
	ds_read_b128 v[8:11], v139 offset:1024
	v_add_co_u32_e32 v12, vcc, s20, v136
	s_mov_b32 s20, 0xa0000
	s_nop 0
	v_addc_co_u32_e32 v13, vcc, 0, v137, vcc
	s_waitcnt lgkmcnt(0)
	global_store_dwordx4 v[12:13], v[8:11], off nt
	ds_read_b128 v[8:11], v139 offset:2048
	v_add_co_u32_e32 v12, vcc, s20, v136
	s_mov_b32 s20, 0xb0000
	s_nop 0
	v_addc_co_u32_e32 v13, vcc, 0, v137, vcc
	s_waitcnt lgkmcnt(0)
	global_store_dwordx4 v[12:13], v[8:11], off nt
	ds_read_b128 v[8:11], v139 offset:3072
	v_add_co_u32_e32 v12, vcc, s20, v136
	s_mov_b32 s20, 0xc0000
	s_nop 0
	v_addc_co_u32_e32 v13, vcc, 0, v137, vcc
	s_waitcnt lgkmcnt(0)
	global_store_dwordx4 v[12:13], v[8:11], off nt
	ds_read_b128 v[8:11], v139 offset:4096
	v_add_co_u32_e32 v12, vcc, s20, v136
	s_mov_b32 s20, 0xd0000
	s_nop 0
	v_addc_co_u32_e32 v13, vcc, 0, v137, vcc
	s_waitcnt lgkmcnt(0)
	global_store_dwordx4 v[12:13], v[8:11], off nt
	ds_read_b128 v[8:11], v139 offset:5120
	v_add_co_u32_e32 v12, vcc, s20, v136
	s_mov_b64 s[22:23], s[16:17]
	s_nop 0
	v_addc_co_u32_e32 v13, vcc, 0, v137, vcc
	s_waitcnt lgkmcnt(0)
	global_store_dwordx4 v[12:13], v[8:11], off nt
	ds_read_b128 v[8:11], v139 offset:6144
	v_add_co_u32_e32 v12, vcc, 0xe0000, v136
	s_nop 1
	v_addc_co_u32_e32 v13, vcc, 0, v137, vcc
	s_waitcnt lgkmcnt(0)
	global_store_dwordx4 v[12:13], v[8:11], off nt
	ds_read_b128 v[8:11], v139 offset:7168
	v_add_co_u32_e32 v12, vcc, 0xf0000, v136
	s_nop 1
	v_addc_co_u32_e32 v13, vcc, 0, v137, vcc
	s_waitcnt lgkmcnt(0)
	global_store_dwordx4 v[12:13], v[8:11], off nt
	s_waitcnt lgkmcnt(0)
	s_waitcnt lgkmcnt(0)
	s_andn2_b64 vcc, exec, s[4:5]
	s_barrier
	s_cbranch_vccz .LBB0_691
